# plus attention loops: removed the compiler's vmcnt(3..0) over-drain ladder before the second-half K/V staging writes (explicit counted wait already covers them; last-iteration path drains in a trampol
# baseline (speedup 1.0000x reference)
; #define SBAR() __builtin_amdgcn_sched_barrier(0)
; #define SLOAD(i, k0) do { sr_[i].vs0 = *reinterpret_cast<const bf16x8*>(&Vh[(long)((k0) + sr) * LDP + sc]); sr_[i].vs1 = *reinterpret_cast<const bf16x8*>(&Vh[(long)((k0) + 32 + sr) * LDP + sc]); \
;     sr_[i].ks0 = *reinterpret_cast<const bf16x8*>(&Kh[(long)((k0) + ksr) * LDP + ksc]); if (DK == 128) sr_[i].ks1 = *reinterpret_cast<const bf16x8*>(&Kh[(long)((k0) + 32 + ksr) * LDP + ksc]); } while (0)
; #define HOOK(P0, P1, j) do { if (NA) na_hook(P0, P1, krow0 + (j), q_row, q_col, win_r, win_c, rpb, inv_scale, hi); } while (0)
; template <int D0> __device__ __forceinline__ void pv_one(f32x16& od, int vb, bf16x8 pa0, bf16x8 pa1, bf16x8 pa2, bf16x8 pa3) {
;   const s16x4 l0 = tr_read<v_rd_off(D0, 0, 0)>(vb), h0 = tr_read<v_rd_off(D0, 0, 1)>(vb), l1 = tr_read<v_rd_off(D0, 1, 0)>(vb), h1 = tr_read<v_rd_off(D0, 1, 1)>(vb);
;   const s16x4 l2 = tr_read<v_rd_off(D0, 2, 0)>(vb), h2 = tr_read<v_rd_off(D0, 2, 1)>(vb), l3 = tr_read<v_rd_off(D0, 3, 0)>(vb), h3 = tr_read<v_rd_off(D0, 3, 1)>(vb);
;   asm volatile("s_waitcnt lgkmcnt(0)" ::: "memory"); SBAR();
;     ...
;   od = __builtin_amdgcn_mfma_f32_32x32x16_bf16(pa0, PK(l0, h0), od, 0, 0, 0);
;   od = __builtin_amdgcn_mfma_f32_32x32x16_bf16(pa1, PK(l1, h1), od, 0, 0, 0);
;   od = __builtin_amdgcn_mfma_f32_32x32x16_bf16(pa2, PK(l2, h2), od, 0, 0, 0);
;   od = __builtin_amdgcn_mfma_f32_32x32x16_bf16(pa3, PK(l3, h3), od, 0, 0, 0);
;     ...
; }
; __device__ __forceinline__ void pv_d0(f32x16* o, int vb, bf16x8 pa0, bf16x8 pa1, bf16x8 pa2, bf16x8 pa3) {
;   pv_one<0>(o[0], vb, pa0, pa1, pa2, pa3); pv_one<1>(o[1], vb, pa0, pa1, pa2, pa3); pv_one<2>(o[2], vb, pa0, pa1, pa2, pa3); pv_one<3>(o[3], vb, pa0, pa1, pa2, pa3);
; template <int DK, bool NA, bool QL, int SD> ...
;     ...
;     pv_d0(o, vb0, pa0, pa1, pa2, pa3); partialSM(pB0, pB1, m_reg, mnB, alB, C, thrRaw);
;     __syncthreads(); SWAIT(); SWRITE(0, SE);
;     RESC(alB); __syncthreads();
;     SBAR(); qkt<DK, QL>(pA0, pA1, K_lds, qr, ql, r32, hi); HOOK(pA0, pA1, j + 1);
;     finishSM(pB0, pB1, alB, l_reg, pa0, pa1, pa2, pa3); SBAR();
;     if (SD == 1 || j + 3 < NT) SLOAD(SE, (j + 1 + SD) * KVBLK); SBAR();
;     pv_d0(o, vb0 + (int)SHM_V, pa0, pa1, pa2, pa3); partialSM(pA0, pA1, m_reg, mnA, alA, C, thrRaw);
;     __syncthreads(); SWAIT(); SWRITE(1, SO);
;     RESC(alA); __syncthreads();
.LBB0_666:
	ds_read_b64_tr_b16 v[220:221], v151 offset:0
	ds_read_b64_tr_b16 v[222:223], v151 offset:0x800
	ds_read_b64_tr_b16 v[224:225], v151 offset:0x1000
	ds_read_b64_tr_b16 v[226:227], v151 offset:0x1800
	ds_read_b64_tr_b16 v[228:229], v151 offset:0x2000
	ds_read_b64_tr_b16 v[230:231], v151 offset:0x2800
	ds_read_b64_tr_b16 v[232:233], v151 offset:0x3000
	ds_read_b64_tr_b16 v[234:235], v151 offset:0x3800
	s_waitcnt lgkmcnt(0)
	s_nop 0
	v_mfma_f32_32x32x16_bf16 v[18:33], v[130:133], v[220:223], v[18:33]
	ds_read_b64_tr_b16 v[220:221], v151 offset:0x200
	ds_read_b64_tr_b16 v[222:223], v151 offset:0xa00
	v_mfma_f32_32x32x16_bf16 v[18:33], v[134:137], v[224:227], v[18:33]
	ds_read_b64_tr_b16 v[224:225], v151 offset:0x1200
	ds_read_b64_tr_b16 v[226:227], v151 offset:0x1a00
	v_mfma_f32_32x32x16_bf16 v[18:33], v[138:141], v[228:231], v[18:33]
	ds_read_b64_tr_b16 v[228:229], v151 offset:0x2200
	ds_read_b64_tr_b16 v[230:231], v151 offset:0x2a00
	v_mfma_f32_32x32x16_bf16 v[18:33], v[142:145], v[232:235], v[18:33]
	ds_read_b64_tr_b16 v[232:233], v151 offset:0x3200
	ds_read_b64_tr_b16 v[234:235], v151 offset:0x3a00
	s_waitcnt lgkmcnt(0)
	v_mfma_f32_32x32x16_bf16 v[50:65], v[130:133], v[220:223], v[50:65]
	ds_read_b64_tr_b16 v[220:221], v151 offset:0x400
	ds_read_b64_tr_b16 v[222:223], v151 offset:0xc00
	v_mfma_f32_32x32x16_bf16 v[50:65], v[134:137], v[224:227], v[50:65]
	ds_read_b64_tr_b16 v[224:225], v151 offset:0x1400
	ds_read_b64_tr_b16 v[226:227], v151 offset:0x1c00
	v_mfma_f32_32x32x16_bf16 v[50:65], v[138:141], v[228:231], v[50:65]
	ds_read_b64_tr_b16 v[228:229], v151 offset:0x2400
	ds_read_b64_tr_b16 v[230:231], v151 offset:0x2c00
	v_mfma_f32_32x32x16_bf16 v[50:65], v[142:145], v[232:235], v[50:65]
	ds_read_b64_tr_b16 v[232:233], v151 offset:0x3400
	ds_read_b64_tr_b16 v[234:235], v151 offset:0x3c00
	s_waitcnt lgkmcnt(0)
	v_mfma_f32_32x32x16_bf16 v[2:17], v[130:133], v[220:223], v[2:17]
	ds_read_b64_tr_b16 v[220:221], v151 offset:0x600
	ds_read_b64_tr_b16 v[222:223], v151 offset:0xe00
	v_mfma_f32_32x32x16_bf16 v[2:17], v[134:137], v[224:227], v[2:17]
	ds_read_b64_tr_b16 v[224:225], v151 offset:0x1600
	ds_read_b64_tr_b16 v[226:227], v151 offset:0x1e00
	v_mfma_f32_32x32x16_bf16 v[2:17], v[138:141], v[228:231], v[2:17]
	ds_read_b64_tr_b16 v[228:229], v151 offset:0x2600
	ds_read_b64_tr_b16 v[230:231], v151 offset:0x2e00
	v_mfma_f32_32x32x16_bf16 v[2:17], v[142:145], v[232:235], v[2:17]
	ds_read_b64_tr_b16 v[232:233], v151 offset:0x3600
	ds_read_b64_tr_b16 v[234:235], v151 offset:0x3e00
	s_waitcnt lgkmcnt(0)
	v_mfma_f32_32x32x16_bf16 v[34:49], v[130:133], v[220:223], v[34:49]
	v_max_f32_e32 v130, v83, v83
	v_max_f32_e32 v131, v82, v82
	v_max_f32_e32 v130, v131, v130
	v_max3_f32 v130, v130, v84, v85
	v_max3_f32 v130, v130, v86, v87
	v_max3_f32 v130, v130, v88, v89
	v_max3_f32 v130, v130, v90, v91
	v_max3_f32 v130, v130, v92, v93
	v_max3_f32 v130, v130, v94, v95
	v_mfma_f32_32x32x16_bf16 v[34:49], v[134:137], v[224:227], v[34:49]
	v_max3_f32 v130, v130, v96, v97
	v_max3_f32 v130, v130, v66, v67
	v_max3_f32 v130, v130, v68, v69
	v_max3_f32 v130, v130, v70, v71
	v_max3_f32 v130, v130, v72, v73
	v_max3_f32 v130, v130, v74, v75
	v_max3_f32 v130, v130, v76, v77
	v_max3_f32 v130, v130, v78, v79
	v_mfma_f32_32x32x16_bf16 v[34:49], v[138:141], v[228:231], v[34:49]
	v_max3_f32 v130, v130, v80, v81
	v_mov_b32_e32 v131, v130
	s_nop 1
	v_permlane32_swap_b32_e32 v130, v131
	v_max_f32_e32 v131, v131, v131
	v_max_f32_e32 v130, v130, v130
	v_max_f32_e32 v130, v130, v131
	v_sub_f32_e32 v131, v130, v215
	s_mov_b32 s2, 0x42b504f3
	v_cmp_ge_f32_e32 vcc, s2, v131
	v_max_f32_e32 v131, v215, v215
	v_max_f32_e32 v131, v131, v130
	v_mfma_f32_32x32x16_bf16 v[34:49], v[142:145], v[232:235], v[34:49]
	v_sub_f32_e32 v130, v215, v131
	v_mul_f32_e32 v130, 0x3e0293ee, v130
	v_exp_f32_e32 v130, v130
	s_cmp_eq_u64 vcc, exec
	s_cselect_b64 s[2:3], -1, 0
	s_barrier
	s_waitcnt vmcnt(4)
	v_cndmask_b32_e64 v130, v130, 1.0, s[2:3]
	v_cmp_gt_f32_e32 vcc, 1.0, v130
	ds_write_b128 v209, v[114:117] offset:16384
	ds_write_b128 v210, v[126:129] offset:16384
	ds_write_b128 v177, v[118:121] offset:49152
	ds_write_b128 v208, v[122:125] offset:49152
	s_cbranch_vccz .LBB0_670
	s_and_saveexec_b64 s[6:7], s[0:1]
	ds_write_b32 v149, v130 offset:128
	s_or_b64 exec, exec, s[6:7]
	s_waitcnt lgkmcnt(0)
	v_add_u32_e32 v126, v148, v0
	ds_read_b128 v[114:117], v126 offset:128
	ds_read_b128 v[118:121], v126 offset:160
	ds_read_b128 v[122:125], v126 offset:192
	ds_read_b128 v[126:129], v126 offset:224
	s_waitcnt lgkmcnt(3)
	v_pk_mul_f32 v[50:51], v[114:115], v[50:51]
	v_pk_mul_f32 v[52:53], v[52:53], v[116:117]
	s_waitcnt lgkmcnt(2)
	v_pk_mul_f32 v[54:55], v[54:55], v[118:119]
	v_pk_mul_f32 v[56:57], v[56:57], v[120:121]
	s_waitcnt lgkmcnt(1)
	v_pk_mul_f32 v[58:59], v[58:59], v[122:123]
	v_pk_mul_f32 v[60:61], v[60:61], v[124:125]
	s_waitcnt lgkmcnt(0)
	v_pk_mul_f32 v[62:63], v[62:63], v[126:127]
	v_pk_mul_f32 v[30:31], v[30:31], v[126:127]
	v_pk_mul_f32 v[26:27], v[26:27], v[122:123]
	v_pk_mul_f32 v[22:23], v[22:23], v[118:119]
	v_pk_mul_f32 v[32:33], v[32:33], v[128:129]
	v_pk_mul_f32 v[28:29], v[28:29], v[124:125]
	v_pk_mul_f32 v[24:25], v[24:25], v[120:121]
	v_pk_mul_f32 v[20:21], v[20:21], v[116:117]
	v_pk_mul_f32 v[18:19], v[18:19], v[114:115]
	v_pk_mul_f32 v[64:65], v[64:65], v[128:129]
	v_pk_mul_f32 v[34:35], v[114:115], v[34:35]
	v_pk_mul_f32 v[36:37], v[36:37], v[116:117]
	v_pk_mul_f32 v[38:39], v[38:39], v[118:119]
	v_pk_mul_f32 v[40:41], v[40:41], v[120:121]
	v_pk_mul_f32 v[42:43], v[42:43], v[122:123]
	v_pk_mul_f32 v[44:45], v[44:45], v[124:125]
	v_pk_mul_f32 v[46:47], v[46:47], v[126:127]
	v_pk_mul_f32 v[14:15], v[14:15], v[126:127]
	v_pk_mul_f32 v[10:11], v[10:11], v[122:123]
	v_pk_mul_f32 v[6:7], v[6:7], v[118:119]
	v_pk_mul_f32 v[16:17], v[16:17], v[128:129]
	v_pk_mul_f32 v[12:13], v[12:13], v[124:125]
	v_pk_mul_f32 v[8:9], v[8:9], v[120:121]
	v_pk_mul_f32 v[4:5], v[4:5], v[116:117]
	v_pk_mul_f32 v[2:3], v[2:3], v[114:115]
	v_pk_mul_f32 v[48:49], v[48:49], v[128:129]

; #define SBAR() __builtin_amdgcn_sched_barrier(0)
; #define SLOAD(i, k0) do { sr_[i].vs0 = *reinterpret_cast<const bf16x8*>(&Vh[(long)((k0) + sr) * LDP + sc]); sr_[i].vs1 = *reinterpret_cast<const bf16x8*>(&Vh[(long)((k0) + 32 + sr) * LDP + sc]); \
;     sr_[i].ks0 = *reinterpret_cast<const bf16x8*>(&Kh[(long)((k0) + ksr) * LDP + ksc]); if (DK == 128) sr_[i].ks1 = *reinterpret_cast<const bf16x8*>(&Kh[(long)((k0) + 32 + ksr) * LDP + ksc]); } while (0)
; #define SWAIT() do { if (SD == 1) asm volatile("s_waitcnt vmcnt(0)" ::: "memory"); else if (DK == 128) asm volatile("s_waitcnt vmcnt(4)" ::: "memory"); else asm volatile("s_waitcnt vmcnt(3)" ::: "memory"); } while (0)
; #define RESC(a) do { if (__any((a) < 1.f)) { if (hi == 0) al_l[r32] = (a); asm volatile("s_waitcnt lgkmcnt(0)" ::: "memory"); \
;     _Pragma("unroll") for (int d = 0; d < 4; ++d) _Pragma("unroll") for (int r = 0; r < 16; ++r) o[d][r] *= al_l[crow(r, hi)]; } } while (0)
; #define HOOK(P0, P1, j) do { if (NA) na_hook(P0, P1, krow0 + (j), q_row, q_col, win_r, win_c, rpb, inv_scale, hi); } while (0)
; template <int DK, bool NA, bool QL, int SD> ...
;     ...
;     __syncthreads(); SWAIT(); SWRITE(0, SE);
;     RESC(alB); __syncthreads();
;     SBAR(); qkt<DK, QL>(pA0, pA1, K_lds, qr, ql, r32, hi); HOOK(pA0, pA1, j + 1);
;     finishSM(pB0, pB1, alB, l_reg, pa0, pa1, pa2, pa3); SBAR();
;     if (SD == 1 || j + 3 < NT) SLOAD(SE, (j + 1 + SD) * KVBLK); SBAR();
.Lod_gqa:
	s_waitcnt vmcnt(0)
	s_branch .LBB0_666

; #define SWAIT() do { if (SD == 1) asm volatile("s_waitcnt vmcnt(0)" ::: "memory"); else if (DK == 128) asm volatile("s_waitcnt vmcnt(4)" ::: "memory"); else asm volatile("s_waitcnt vmcnt(3)" ::: "memory"); } while (0)
; #define RESC(a) do { if (__any((a) < 1.f)) { if (hi == 0) al_l[r32] = (a); asm volatile("s_waitcnt lgkmcnt(0)" ::: "memory"); \
;     _Pragma("unroll") for (int d = 0; d < 4; ++d) _Pragma("unroll") for (int r = 0; r < 16; ++r) o[d][r] *= al_l[crow(r, hi)]; } } while (0)
; __device__ __forceinline__ void partialSM(f32x16& p0, f32x16& p1, float& m_reg, float& mn, float& alpha, float C, float thrRaw) {
;   float pmax = p0[0];
; #pragma unroll
;   for (int r = 1; r < 16; ++r) pmax = fmaxf(pmax, p0[r]);
; #pragma unroll
;   for (int r = 0; r < 16; ++r) pmax = fmaxf(pmax, p1[r]);
;   { auto rr = __builtin_amdgcn_permlane32_swap(__float_as_uint(pmax), __float_as_uint(pmax), false, false);
;     pmax = fmaxf(__uint_as_float(rr[0]), __uint_as_float(rr[1])); }
;   if (__builtin_expect(__all(pmax - m_reg <= thrRaw), 1)) { mn = m_reg; alpha = 1.f; }
;   else { mn = fmaxf(m_reg, pmax); alpha = __builtin_amdgcn_exp2f((m_reg - mn) * C); m_reg = mn; }
;   float mnC = -mn * C;
; #pragma unroll
;   for (int r = 0; r < 16; ++r) p0[r] = fmaf(p0[r], C, mnC);
; #pragma unroll
;   for (int r = 0; r < 16; ++r) p1[r] = fmaf(p1[r], C, mnC);
; #pragma unroll
;   for (int r = 0; r < 16; ++r) p0[r] = __builtin_amdgcn_exp2f(p0[r]);
; template <int DK, bool NA, bool QL, int SD> ...
;     ...
;     pv_d0(o, vb0 + (int)SHM_V, pa0, pa1, pa2, pa3); partialSM(pA0, pA1, m_reg, mnA, alA, C, thrRaw);
;     __syncthreads(); SWAIT(); SWRITE(1, SO);
;     RESC(alA); __syncthreads();
.LBB0_688:
	ds_read_b64_tr_b16 v[226:227], v210 offset:0
	ds_read_b64_tr_b16 v[228:229], v210 offset:0x800
	ds_read_b64_tr_b16 v[230:231], v210 offset:0x1000
	ds_read_b64_tr_b16 v[232:233], v210 offset:0x1800
	ds_read_b64_tr_b16 v[234:235], v210 offset:0x2000
	ds_read_b64_tr_b16 v[236:237], v210 offset:0x2800
	ds_read_b64_tr_b16 v[238:239], v210 offset:0x3000
	ds_read_b64_tr_b16 v[240:241], v210 offset:0x3800
	s_waitcnt lgkmcnt(0)
	s_nop 0
	v_mfma_f32_32x32x16_bf16 v[18:33], v[138:141], v[226:229], v[18:33]
	ds_read_b64_tr_b16 v[226:227], v210 offset:0x200
	ds_read_b64_tr_b16 v[228:229], v210 offset:0xa00
	v_mfma_f32_32x32x16_bf16 v[18:33], v[142:145], v[230:233], v[18:33]
	ds_read_b64_tr_b16 v[230:231], v210 offset:0x1200
	ds_read_b64_tr_b16 v[232:233], v210 offset:0x1a00
	v_mfma_f32_32x32x16_bf16 v[18:33], v[146:149], v[234:237], v[18:33]
	ds_read_b64_tr_b16 v[234:235], v210 offset:0x2200
	ds_read_b64_tr_b16 v[236:237], v210 offset:0x2a00
	v_mfma_f32_32x32x16_bf16 v[18:33], v[150:153], v[238:241], v[18:33]
	ds_read_b64_tr_b16 v[238:239], v210 offset:0x3200
	ds_read_b64_tr_b16 v[240:241], v210 offset:0x3a00
	s_waitcnt lgkmcnt(0)
	v_mfma_f32_32x32x16_bf16 v[2:17], v[138:141], v[226:229], v[2:17]
	ds_read_b64_tr_b16 v[226:227], v210 offset:0x400
	ds_read_b64_tr_b16 v[228:229], v210 offset:0xc00
	v_mfma_f32_32x32x16_bf16 v[2:17], v[142:145], v[230:233], v[2:17]
	ds_read_b64_tr_b16 v[230:231], v210 offset:0x1400
	ds_read_b64_tr_b16 v[232:233], v210 offset:0x1c00
	v_mfma_f32_32x32x16_bf16 v[2:17], v[146:149], v[234:237], v[2:17]
	ds_read_b64_tr_b16 v[234:235], v210 offset:0x2400
	ds_read_b64_tr_b16 v[236:237], v210 offset:0x2c00
	v_mfma_f32_32x32x16_bf16 v[2:17], v[150:153], v[238:241], v[2:17]
	ds_read_b64_tr_b16 v[238:239], v210 offset:0x3400
	ds_read_b64_tr_b16 v[240:241], v210 offset:0x3c00
	s_waitcnt lgkmcnt(0)
	v_mfma_f32_32x32x16_bf16 v[50:65], v[138:141], v[226:229], v[50:65]
	ds_read_b64_tr_b16 v[226:227], v210 offset:0x600
	ds_read_b64_tr_b16 v[228:229], v210 offset:0xe00
	v_mfma_f32_32x32x16_bf16 v[50:65], v[142:145], v[230:233], v[50:65]
	ds_read_b64_tr_b16 v[230:231], v210 offset:0x1600
	ds_read_b64_tr_b16 v[232:233], v210 offset:0x1e00
	v_mfma_f32_32x32x16_bf16 v[50:65], v[146:149], v[234:237], v[50:65]
	ds_read_b64_tr_b16 v[234:235], v210 offset:0x2600
	ds_read_b64_tr_b16 v[236:237], v210 offset:0x2e00
	v_mfma_f32_32x32x16_bf16 v[50:65], v[150:153], v[238:241], v[50:65]
	ds_read_b64_tr_b16 v[238:239], v210 offset:0x3600
	ds_read_b64_tr_b16 v[240:241], v210 offset:0x3e00
	s_waitcnt lgkmcnt(0)
	v_mfma_f32_32x32x16_bf16 v[34:49], v[138:141], v[226:229], v[34:49]
	v_max_f32_e32 v138, v83, v83
	v_max_f32_e32 v139, v82, v82
	v_max_f32_e32 v138, v139, v138
	v_max3_f32 v138, v138, v84, v85
	v_max3_f32 v138, v138, v86, v87
	v_max3_f32 v138, v138, v88, v89
	v_max3_f32 v138, v138, v90, v91
	v_max3_f32 v138, v138, v92, v93
	v_max3_f32 v138, v138, v94, v95
	v_mfma_f32_32x32x16_bf16 v[34:49], v[142:145], v[230:233], v[34:49]
	v_max3_f32 v138, v138, v96, v97
	v_max3_f32 v138, v138, v66, v67
	v_max3_f32 v138, v138, v68, v69
	v_max3_f32 v138, v138, v70, v71
	v_max3_f32 v138, v138, v72, v73
	v_max3_f32 v138, v138, v74, v75
	v_max3_f32 v138, v138, v76, v77
	v_max3_f32 v138, v138, v78, v79
	v_mfma_f32_32x32x16_bf16 v[34:49], v[146:149], v[234:237], v[34:49]
	v_max3_f32 v138, v138, v80, v81
	v_mov_b32_e32 v139, v138
	s_nop 1
	v_permlane32_swap_b32_e32 v138, v139
	v_max_f32_e32 v139, v139, v139
	v_max_f32_e32 v138, v138, v138
	v_max_f32_e32 v138, v138, v139
	v_sub_f32_e32 v139, v138, v223
	s_mov_b32 s2, 0x42800000
	v_cmp_ge_f32_e32 vcc, s2, v139
	v_max_f32_e32 v139, v223, v223
	v_max_f32_e32 v138, v139, v138
	v_mfma_f32_32x32x16_bf16 v[34:49], v[150:153], v[238:241], v[34:49]
	v_sub_f32_e32 v139, v223, v138
	v_mul_f32_e32 v139, 0x3e38aa3b, v139
	v_exp_f32_e32 v139, v139
	s_cmp_eq_u64 vcc, exec
	s_cselect_b64 s[2:3], -1, 0
	s_barrier
	s_waitcnt vmcnt(3)
	v_cndmask_b32_e64 v143, v139, 1.0, s[2:3]
	v_cmp_gt_f32_e32 vcc, 1.0, v143
	ds_write_b128 v214, v[126:129] offset:16384
	ds_write_b128 v215, v[130:133] offset:16384
	ds_write_b128 v213, v[134:137] offset:49152
	s_cbranch_vccz .LBB0_692
	s_and_saveexec_b64 s[6:7], s[0:1]
	ds_write_b32 v208, v143 offset:128
	s_or_b64 exec, exec, s[6:7]
	s_waitcnt lgkmcnt(0)
	v_add_u32_e32 v139, v207, v0
	ds_read_b128 v[126:129], v139 offset:128
	ds_read_b128 v[130:133], v139 offset:160
	ds_read_b128 v[134:137], v139 offset:224
	ds_read_b128 v[144:147], v139 offset:192
	s_waitcnt lgkmcnt(3)
	v_pk_mul_f32 v[50:51], v[126:127], v[50:51]
	v_pk_mul_f32 v[52:53], v[128:129], v[52:53]
	s_waitcnt lgkmcnt(2)
	v_pk_mul_f32 v[54:55], v[130:131], v[54:55]
	s_waitcnt lgkmcnt(1)
	v_pk_mul_f32 v[30:31], v[30:31], v[134:135]
	s_waitcnt lgkmcnt(0)
	v_pk_mul_f32 v[26:27], v[26:27], v[144:145]
	v_pk_mul_f32 v[22:23], v[22:23], v[130:131]
	v_pk_mul_f32 v[32:33], v[32:33], v[136:137]
	v_pk_mul_f32 v[28:29], v[28:29], v[146:147]
	v_pk_mul_f32 v[24:25], v[24:25], v[132:133]
	v_pk_mul_f32 v[20:21], v[20:21], v[128:129]
	v_pk_mul_f32 v[18:19], v[18:19], v[126:127]
	v_pk_mul_f32 v[14:15], v[134:135], v[14:15]
	v_pk_mul_f32 v[10:11], v[144:145], v[10:11]
	v_pk_mul_f32 v[6:7], v[130:131], v[6:7]
	v_pk_mul_f32 v[16:17], v[136:137], v[16:17]
	v_pk_mul_f32 v[12:13], v[146:147], v[12:13]
	v_pk_mul_f32 v[8:9], v[132:133], v[8:9]
	v_pk_mul_f32 v[4:5], v[128:129], v[4:5]
	v_pk_mul_f32 v[2:3], v[126:127], v[2:3]
	v_pk_mul_f32 v[56:57], v[132:133], v[56:57]
	v_pk_mul_f32 v[34:35], v[126:127], v[34:35]
	v_pk_mul_f32 v[36:37], v[36:37], v[128:129]
	v_pk_mul_f32 v[38:39], v[38:39], v[130:131]
	v_pk_mul_f32 v[40:41], v[40:41], v[132:133]
	v_pk_mul_f32 v[58:59], v[58:59], v[144:145]
	v_pk_mul_f32 v[42:43], v[42:43], v[144:145]
	v_pk_mul_f32 v[60:61], v[60:61], v[146:147]
	v_pk_mul_f32 v[44:45], v[44:45], v[146:147]
	v_pk_mul_f32 v[62:63], v[62:63], v[134:135]
	v_pk_mul_f32 v[46:47], v[46:47], v[134:135]
	v_pk_mul_f32 v[64:65], v[64:65], v[136:137]
	v_pk_mul_f32 v[48:49], v[48:49], v[136:137]

; #define SWAIT() do { if (SD == 1) asm volatile("s_waitcnt vmcnt(0)" ::: "memory"); else if (DK == 128) asm volatile("s_waitcnt vmcnt(4)" ::: "memory"); else asm volatile("s_waitcnt vmcnt(3)" ::: "memory"); } while (0)
; #define RESC(a) do { if (__any((a) < 1.f)) { if (hi == 0) al_l[r32] = (a); asm volatile("s_waitcnt lgkmcnt(0)" ::: "memory"); \
;     _Pragma("unroll") for (int d = 0; d < 4; ++d) _Pragma("unroll") for (int r = 0; r < 16; ++r) o[d][r] *= al_l[crow(r, hi)]; } } while (0)
; __device__ __forceinline__ void partialSM(f32x16& p0, f32x16& p1, float& m_reg, float& mn, float& alpha, float C, float thrRaw) {
;   float pmax = p0[0];
; #pragma unroll
;   for (int r = 1; r < 16; ++r) pmax = fmaxf(pmax, p0[r]);
; #pragma unroll
;   for (int r = 0; r < 16; ++r) pmax = fmaxf(pmax, p1[r]);
;   { auto rr = __builtin_amdgcn_permlane32_swap(__float_as_uint(pmax), __float_as_uint(pmax), false, false);
;     pmax = fmaxf(__uint_as_float(rr[0]), __uint_as_float(rr[1])); }
;   if (__builtin_expect(__all(pmax - m_reg <= thrRaw), 1)) { mn = m_reg; alpha = 1.f; }
;   else { mn = fmaxf(m_reg, pmax); alpha = __builtin_amdgcn_exp2f((m_reg - mn) * C); m_reg = mn; }
;   float mnC = -mn * C;
; #pragma unroll
;   for (int r = 0; r < 16; ++r) p0[r] = fmaf(p0[r], C, mnC);
; #pragma unroll
;   for (int r = 0; r < 16; ++r) p1[r] = fmaf(p1[r], C, mnC);
; #pragma unroll
;   for (int r = 0; r < 16; ++r) p0[r] = __builtin_amdgcn_exp2f(p0[r]);
; template <int DK, bool NA, bool QL, int SD> ...
;     ...
;     pv_d0(o, vb0 + (int)SHM_V, pa0, pa1, pa2, pa3); partialSM(pA0, pA1, m_reg, mnA, alA, C, thrRaw);
;     __syncthreads(); SWAIT(); SWRITE(1, SO);
;     RESC(alA); __syncthreads();
.LBB0_707:
	ds_read_b64_tr_b16 v[226:227], v210 offset:0
	ds_read_b64_tr_b16 v[228:229], v210 offset:0x800
	ds_read_b64_tr_b16 v[230:231], v210 offset:0x1000
	ds_read_b64_tr_b16 v[232:233], v210 offset:0x1800
	ds_read_b64_tr_b16 v[234:235], v210 offset:0x2000
	ds_read_b64_tr_b16 v[236:237], v210 offset:0x2800
	ds_read_b64_tr_b16 v[238:239], v210 offset:0x3000
	ds_read_b64_tr_b16 v[240:241], v210 offset:0x3800
	s_waitcnt lgkmcnt(0)
	s_nop 0
	v_mfma_f32_32x32x16_bf16 v[2:17], v[138:141], v[226:229], v[2:17]
	ds_read_b64_tr_b16 v[226:227], v210 offset:0x200
	ds_read_b64_tr_b16 v[228:229], v210 offset:0xa00
	v_mfma_f32_32x32x16_bf16 v[2:17], v[142:145], v[230:233], v[2:17]
	ds_read_b64_tr_b16 v[230:231], v210 offset:0x1200
	ds_read_b64_tr_b16 v[232:233], v210 offset:0x1a00
	v_mfma_f32_32x32x16_bf16 v[2:17], v[146:149], v[234:237], v[2:17]
	ds_read_b64_tr_b16 v[234:235], v210 offset:0x2200
	ds_read_b64_tr_b16 v[236:237], v210 offset:0x2a00
	v_mfma_f32_32x32x16_bf16 v[2:17], v[150:153], v[238:241], v[2:17]
	ds_read_b64_tr_b16 v[238:239], v210 offset:0x3200
	ds_read_b64_tr_b16 v[240:241], v210 offset:0x3a00
	s_waitcnt lgkmcnt(0)
	v_mfma_f32_32x32x16_bf16 v[50:65], v[138:141], v[226:229], v[50:65]
	ds_read_b64_tr_b16 v[226:227], v210 offset:0x400
	ds_read_b64_tr_b16 v[228:229], v210 offset:0xc00
	v_mfma_f32_32x32x16_bf16 v[50:65], v[142:145], v[230:233], v[50:65]
	ds_read_b64_tr_b16 v[230:231], v210 offset:0x1400
	ds_read_b64_tr_b16 v[232:233], v210 offset:0x1c00
	v_mfma_f32_32x32x16_bf16 v[50:65], v[146:149], v[234:237], v[50:65]
	ds_read_b64_tr_b16 v[234:235], v210 offset:0x2400
	ds_read_b64_tr_b16 v[236:237], v210 offset:0x2c00
	v_mfma_f32_32x32x16_bf16 v[50:65], v[150:153], v[238:241], v[50:65]
	ds_read_b64_tr_b16 v[238:239], v210 offset:0x3400
	ds_read_b64_tr_b16 v[240:241], v210 offset:0x3c00
	s_waitcnt lgkmcnt(0)
	v_mfma_f32_32x32x16_bf16 v[34:49], v[138:141], v[226:229], v[34:49]
	ds_read_b64_tr_b16 v[226:227], v210 offset:0x600
	ds_read_b64_tr_b16 v[228:229], v210 offset:0xe00
	v_mfma_f32_32x32x16_bf16 v[34:49], v[142:145], v[230:233], v[34:49]
	ds_read_b64_tr_b16 v[230:231], v210 offset:0x1600
	ds_read_b64_tr_b16 v[232:233], v210 offset:0x1e00
	v_mfma_f32_32x32x16_bf16 v[34:49], v[146:149], v[234:237], v[34:49]
	ds_read_b64_tr_b16 v[234:235], v210 offset:0x2600
	ds_read_b64_tr_b16 v[236:237], v210 offset:0x2e00
	v_mfma_f32_32x32x16_bf16 v[34:49], v[150:153], v[238:241], v[34:49]
	ds_read_b64_tr_b16 v[238:239], v210 offset:0x3600
	ds_read_b64_tr_b16 v[240:241], v210 offset:0x3e00
	s_waitcnt lgkmcnt(0)
	v_mfma_f32_32x32x16_bf16 v[18:33], v[138:141], v[226:229], v[18:33]
	v_max_f32_e32 v138, v83, v83
	v_max_f32_e32 v139, v82, v82
	v_max_f32_e32 v138, v139, v138
	v_max3_f32 v138, v138, v84, v85
	v_max3_f32 v138, v138, v86, v87
	v_max3_f32 v138, v138, v88, v89
	v_max3_f32 v138, v138, v90, v91
	v_max3_f32 v138, v138, v92, v93
	v_max3_f32 v138, v138, v94, v95
	v_mfma_f32_32x32x16_bf16 v[18:33], v[142:145], v[230:233], v[18:33]
	v_max3_f32 v138, v138, v96, v97
	v_max3_f32 v138, v138, v66, v67
	v_max3_f32 v138, v138, v68, v69
	v_max3_f32 v138, v138, v70, v71
	v_max3_f32 v138, v138, v72, v73
	v_max3_f32 v138, v138, v74, v75
	v_max3_f32 v138, v138, v76, v77
	v_max3_f32 v138, v138, v78, v79
	v_mfma_f32_32x32x16_bf16 v[18:33], v[146:149], v[234:237], v[18:33]
	v_max3_f32 v138, v138, v80, v81
	v_mov_b32_e32 v139, v138
	s_nop 1
	v_permlane32_swap_b32_e32 v138, v139
	v_max_f32_e32 v139, v139, v139
	v_max_f32_e32 v138, v138, v138
	v_max_f32_e32 v138, v138, v139
	v_sub_f32_e32 v139, v138, v223
	s_mov_b32 s2, 0x42800000
	v_cmp_ge_f32_e32 vcc, s2, v139
	v_max_f32_e32 v139, v223, v223
	v_max_f32_e32 v138, v139, v138
	v_mfma_f32_32x32x16_bf16 v[18:33], v[150:153], v[238:241], v[18:33]
	v_sub_f32_e32 v139, v223, v138
	v_mul_f32_e32 v139, 0x3e38aa3b, v139
	v_exp_f32_e32 v139, v139
	s_cmp_eq_u64 vcc, exec
	s_cselect_b64 s[2:3], -1, 0
	s_barrier
	s_waitcnt vmcnt(3)
	v_cndmask_b32_e64 v143, v139, 1.0, s[2:3]
	v_cmp_gt_f32_e32 vcc, 1.0, v143
	ds_write_b128 v212, v[126:129] offset:16384
	ds_write_b128 v213, v[130:133] offset:16384
	ds_write_b128 v214, v[134:137] offset:49152
	s_cbranch_vccz .LBB0_711
	s_and_saveexec_b64 s[6:7], s[0:1]
	ds_write_b32 v208, v143 offset:128
	s_or_b64 exec, exec, s[6:7]
	s_waitcnt lgkmcnt(0)
	v_add_u32_e32 v139, v207, v0
	ds_read_b128 v[126:129], v139 offset:224
	ds_read_b128 v[130:133], v139 offset:192
	ds_read_b128 v[134:137], v139 offset:160
	ds_read_b128 v[144:147], v139 offset:128
	s_waitcnt lgkmcnt(3)
	v_pk_mul_f32 v[14:15], v[14:15], v[126:127]
	s_waitcnt lgkmcnt(2)
	v_pk_mul_f32 v[10:11], v[10:11], v[130:131]
	s_waitcnt lgkmcnt(1)
	v_pk_mul_f32 v[6:7], v[6:7], v[134:135]
	v_pk_mul_f32 v[16:17], v[16:17], v[128:129]
	v_pk_mul_f32 v[12:13], v[12:13], v[132:133]
	v_pk_mul_f32 v[8:9], v[8:9], v[136:137]
	s_waitcnt lgkmcnt(0)
	v_pk_mul_f32 v[4:5], v[4:5], v[146:147]
	v_pk_mul_f32 v[2:3], v[2:3], v[144:145]
	v_pk_mul_f32 v[62:63], v[126:127], v[62:63]
	v_pk_mul_f32 v[58:59], v[130:131], v[58:59]
	v_pk_mul_f32 v[54:55], v[134:135], v[54:55]
	v_pk_mul_f32 v[64:65], v[128:129], v[64:65]
	v_pk_mul_f32 v[60:61], v[132:133], v[60:61]
	v_pk_mul_f32 v[56:57], v[136:137], v[56:57]
	v_pk_mul_f32 v[52:53], v[146:147], v[52:53]
	v_pk_mul_f32 v[50:51], v[144:145], v[50:51]
	v_pk_mul_f32 v[46:47], v[126:127], v[46:47]
	v_pk_mul_f32 v[42:43], v[130:131], v[42:43]
	v_pk_mul_f32 v[38:39], v[134:135], v[38:39]
	v_pk_mul_f32 v[48:49], v[128:129], v[48:49]
	v_pk_mul_f32 v[44:45], v[132:133], v[44:45]
	v_pk_mul_f32 v[40:41], v[136:137], v[40:41]
	v_pk_mul_f32 v[36:37], v[146:147], v[36:37]
	v_pk_mul_f32 v[34:35], v[144:145], v[34:35]
	v_pk_mul_f32 v[30:31], v[126:127], v[30:31]
	v_pk_mul_f32 v[26:27], v[130:131], v[26:27]
	v_pk_mul_f32 v[22:23], v[134:135], v[22:23]
	v_pk_mul_f32 v[32:33], v[128:129], v[32:33]
	v_pk_mul_f32 v[28:29], v[132:133], v[28:29]
	v_pk_mul_f32 v[24:25], v[136:137], v[24:25]
	v_pk_mul_f32 v[20:21], v[146:147], v[20:21]
	v_pk_mul_f32 v[18:19], v[144:145], v[18:19]
